# GLA state scan: four-chunk trips software-pipelined over two register sets (next trip's 12 loads issued before this trip's dependent updates), counted vmcnt
# speedup vs baseline: 1.0224x; 1.0031x over previous
; __device__ __forceinline__ unsigned pk2(float lo, float hi) { return pg8::cvt_pk_bf16(lo, hi); }
; __device__ __forceinline__ float bflo(unsigned w) { return __uint_as_float(w << 16); }
; __device__ __forceinline__ float bfhi(unsigned w) { return __uint_as_float(w & 0xffff0000u); }
; __device__ __forceinline__ bf16* ub_slot(unsigned char* ybase, int unit, int) { return (bf16*)ybase + (size_t)unit * 32768; }
; __device__ __forceinline__ void gla_scan_vec(unsigned char* ws, int xnrow0, const float* DECB, int lchunk0, int nchunks, int h, int e, const float* s0, float* sout) {
;     const int lane = e & 63, s2 = (e >> 6) & 1, db = (e >> 7) & 3, w = e >> 9, hi = lane >> 5, r32 = lane & 31;
;     const int dbase = 32 * db + 16 * s2 + 4 * hi, v = 32 * w + r32;
;     float S[8];
; #pragma unroll
;     for (int jj = 0; jj < 8; ++jj) S[jj] = s0 ? s0[(size_t)(dbase + 8 * (jj >> 2) + (jj & 3)) * 256 + v] : 0.f;
;     for (int n0 = 0; n0 < nchunks; n0 += 4) {
;         u32x4 uw[4]; f32x4 d0[4], d1[4]; bf16* up[4];
; #pragma unroll
;         for (int q = 0; q < 4; ++q) { const int n = (n0 + q < nchunks) ? n0 + q : nchunks - 1; const int unit = (lchunk0 + n) * 4 + h;
;             up[q] = ub_slot(ws, unit, xnrow0) + (size_t)e * 8; uw[q] = *(const u32x4*)up[q];
;             d0[q] = *(const f32x4*)(DECB + (size_t)unit * 128 + dbase); d1[q] = *(const f32x4*)(DECB + (size_t)unit * 128 + dbase + 8); }
; #pragma unroll
;         for (int q = 0; q < 4; ++q) if (n0 + q < nchunks) {
;             *(u32x4*)up[q] = (u32x4){pk2(S[0], S[1]), pk2(S[2], S[3]), pk2(S[4], S[5]), pk2(S[6], S[7])};
;             S[0] = d0[q][0] * (S[0] + bflo(uw[q].x)); S[1] = d0[q][1] * (S[1] + bfhi(uw[q].x)); S[2] = d0[q][2] * (S[2] + bflo(uw[q].y)); S[3] = d0[q][3] * (S[3] + bfhi(uw[q].y));
;             S[4] = d1[q][0] * (S[4] + bflo(uw[q].z)); S[5] = d1[q][1] * (S[5] + bfhi(uw[q].z)); S[6] = d1[q][2] * (S[6] + bflo(uw[q].w)); S[7] = d1[q][3] * (S[7] + bfhi(uw[q].w)); }
;     }
.LBB0_618:
	v_bfe_u32 v4, v32, 12, 2
	v_ashrrev_i32_e32 v33, 14, v32
	v_lshrrev_b32_e32 v5, 1, v32
	v_lshl_or_b32 v18, v33, 7, v4
	s_load_dwordx4 s[20:23], s[90:91], 0xa8
	v_and_b32_e32 v5, 16, v5
	s_movk_i32 s2, 0x1c0
	v_or_b32_e32 v6, 12, v18
	v_or_b32_e32 v10, 8, v18
	v_or_b32_e32 v14, 4, v18
	v_and_or_b32 v20, v32, s2, v5
	v_lshlrev_b32_e32 v5, 1, v31
	v_ashrrev_i32_e32 v7, 31, v6
	v_ashrrev_i32_e32 v11, 31, v10
	v_ashrrev_i32_e32 v15, 31, v14
	v_ashrrev_i32_e32 v19, 31, v18
	v_and_b32_e32 v21, 0xfff0, v5
	v_lshlrev_b64 v[4:5], 9, v[6:7]
	v_lshlrev_b64 v[6:7], 16, v[6:7]
	v_lshlrev_b64 v[8:9], 9, v[10:11]
	v_lshlrev_b64 v[10:11], 16, v[10:11]
	v_lshlrev_b64 v[12:13], 9, v[14:15]
	v_lshlrev_b64 v[14:15], 16, v[14:15]
	v_lshlrev_b64 v[16:17], 16, v[18:19]
	v_lshlrev_b64 v[18:19], 9, v[18:19]
	v_or_b32_e32 v4, v4, v20
	v_or_b32_e32 v6, v6, v21
	v_or_b32_e32 v8, v8, v20
	v_or_b32_e32 v10, v10, v21
	v_or_b32_e32 v12, v12, v20
	v_or_b32_e32 v14, v14, v21
	v_or_b32_e32 v16, v16, v21
	v_or_b32_e32 v18, v18, v20
	v_mov_b32_e32 v20, 0
	v_lshrrev_b32_e32 v2, 12, v32
	s_waitcnt lgkmcnt(0)
	v_lshl_add_u64 v[4:5], s[20:21], 0, v[4:5]
	v_lshl_add_u64 v[6:7], s[20:21], 0, v[6:7]
	v_lshl_add_u64 v[8:9], s[20:21], 0, v[8:9]
	v_lshl_add_u64 v[10:11], s[20:21], 0, v[10:11]
	v_lshl_add_u64 v[12:13], s[20:21], 0, v[12:13]
	v_lshl_add_u64 v[14:15], s[20:21], 0, v[14:15]
	v_lshl_add_u64 v[16:17], s[20:21], 0, v[16:17]
	v_lshl_add_u64 v[18:19], s[20:21], 0, v[18:19]
	v_mov_b32_e32 v21, v20
	v_mov_b32_e32 v26, v20
	v_mov_b32_e32 v27, v20
	v_mov_b32_e32 v24, v20
	v_mov_b32_e32 v25, v20
	v_mov_b32_e32 v22, v20
	v_mov_b32_e32 v23, v20
	v_lshl_add_u64 v[38:39], v[12:13], 0, s[12:13]
	v_add_co_u32_e32 v42, vcc, s73, v38
	v_lshl_add_u64 v[50:51], v[8:9], 0, s[12:13]
	s_nop 0
	v_addc_co_u32_e32 v43, vcc, 0, v39, vcc
	v_add_co_u32_e32 v54, vcc, s73, v50
	v_lshl_add_u64 v[62:63], v[4:5], 0, s[12:13]
	s_nop 0
	v_addc_co_u32_e32 v55, vcc, 0, v51, vcc
	v_add_co_u32_e32 v66, vcc, s73, v62
	v_lshl_add_u64 v[70:71], v[18:19], 0, s[12:13]
	s_nop 0
	v_addc_co_u32_e32 v67, vcc, 0, v63, vcc
	v_add_co_u32_e32 v74, vcc, s73, v70
	v_lshl_add_u64 v[86:87], v[14:15], 0, s[12:13]
	v_lshl_add_u64 v[88:89], v[10:11], 0, s[12:13]
	v_lshl_add_u64 v[90:91], v[6:7], 0, s[12:13]
	v_addc_co_u32_e32 v75, vcc, 0, v71, vcc
	v_lshl_add_u64 v[92:93], v[16:17], 0, s[12:13]
	global_load_dwordx4 v[34:37], v[86:87], off
	global_load_dwordx4 v[38:41], v[42:43], off
	s_nop 0
	global_load_dwordx4 v[42:45], v[42:43], off offset:32
	global_load_dwordx4 v[46:49], v[88:89], off
	global_load_dwordx4 v[50:53], v[54:55], off
	s_nop 0
	global_load_dwordx4 v[54:57], v[54:55], off offset:32
	global_load_dwordx4 v[58:61], v[90:91], off
	global_load_dwordx4 v[62:65], v[66:67], off
	s_nop 0
	global_load_dwordx4 v[66:69], v[66:67], off offset:32
	s_nop 0
	global_load_dwordx4 v[70:73], v[74:75], off offset:32
	s_nop 0
	global_load_dwordx4 v[74:77], v[74:75], off
	global_load_dwordx4 v[78:81], v[92:93], off
	v_lshl_add_u64 v[4:5], v[4:5], 0, s[86:87]
	v_lshl_add_u64 v[6:7], v[6:7], 0, s[84:85]
	v_lshl_add_u64 v[8:9], v[8:9], 0, s[86:87]
	v_lshl_add_u64 v[10:11], v[10:11], 0, s[84:85]
	v_lshl_add_u64 v[12:13], v[12:13], 0, s[86:87]
	v_lshl_add_u64 v[14:15], v[14:15], 0, s[84:85]
	v_lshl_add_u64 v[16:17], v[16:17], 0, s[84:85]
	v_lshl_add_u64 v[18:19], v[18:19], 0, s[86:87]
	s_mov_b32 s2, 0
.Lscan_pipe:
	v_lshl_add_u64 v[174:175], v[12:13], 0, s[12:13]
	v_add_co_u32_e32 v182, vcc, s73, v174
	v_lshl_add_u64 v[190:191], v[8:9], 0, s[12:13]
	s_nop 0
	v_addc_co_u32_e32 v183, vcc, 0, v175, vcc
	v_add_co_u32_e32 v218, vcc, s73, v190
	v_lshl_add_u64 v[226:227], v[4:5], 0, s[12:13]
	s_nop 0
	v_addc_co_u32_e32 v219, vcc, 0, v191, vcc
	v_add_co_u32_e32 v230, vcc, s73, v226
	v_lshl_add_u64 v[234:235], v[18:19], 0, s[12:13]
	s_nop 0
	v_addc_co_u32_e32 v231, vcc, 0, v227, vcc
	v_add_co_u32_e32 v238, vcc, s73, v234
	v_lshl_add_u64 v[178:179], v[14:15], 0, s[12:13]
	v_lshl_add_u64 v[194:195], v[10:11], 0, s[12:13]
	v_lshl_add_u64 v[246:247], v[6:7], 0, s[12:13]
	v_addc_co_u32_e32 v239, vcc, 0, v235, vcc
	v_lshl_add_u64 v[248:249], v[16:17], 0, s[12:13]
	global_load_dwordx4 v[170:173], v[178:179], off
	global_load_dwordx4 v[174:177], v[182:183], off
	s_nop 0
	global_load_dwordx4 v[182:185], v[182:183], off offset:32
	global_load_dwordx4 v[186:189], v[194:195], off
	global_load_dwordx4 v[190:193], v[218:219], off
	s_nop 0
	global_load_dwordx4 v[218:221], v[218:219], off offset:32
	global_load_dwordx4 v[222:225], v[246:247], off
	global_load_dwordx4 v[226:229], v[230:231], off
	s_nop 0
	global_load_dwordx4 v[230:233], v[230:231], off offset:32
	s_nop 0
	global_load_dwordx4 v[234:237], v[238:239], off offset:32
	s_nop 0
	global_load_dwordx4 v[238:241], v[238:239], off
	global_load_dwordx4 v[242:245], v[248:249], off
	v_lshl_add_u64 v[4:5], v[4:5], 0, s[86:87]
	v_lshl_add_u64 v[6:7], v[6:7], 0, s[84:85]
	v_lshl_add_u64 v[8:9], v[8:9], 0, s[86:87]
	v_lshl_add_u64 v[10:11], v[10:11], 0, s[84:85]
	v_lshl_add_u64 v[12:13], v[12:13], 0, s[86:87]
	v_lshl_add_u64 v[14:15], v[14:15], 0, s[84:85]
	v_lshl_add_u64 v[16:17], v[16:17], 0, s[84:85]
	v_lshl_add_u64 v[18:19], v[18:19], 0, s[86:87]
	v_cvt_pk_bf16_f32 v82, v26, v27
	v_cvt_pk_bf16_f32 v83, v24, v25
	v_cvt_pk_bf16_f32 v84, v22, v23
	v_cvt_pk_bf16_f32 v85, v20, v21
	global_store_dwordx4 v[92:93], v[82:85], off
	s_nop 1
	s_cmp_eq_u32 s2, 0
	s_cbranch_scc1 .Lscan_w0
	s_waitcnt vmcnt(17)
	s_branch .Lscan_w1
.Lscan_w0:
	s_waitcnt vmcnt(13)
; __device__ __forceinline__ unsigned pk2(float lo, float hi) { return pg8::cvt_pk_bf16(lo, hi); }
; __device__ __forceinline__ float bflo(unsigned w) { return __uint_as_float(w << 16); }
; __device__ __forceinline__ float bfhi(unsigned w) { return __uint_as_float(w & 0xffff0000u); }
; __device__ __forceinline__ void gla_scan_vec(unsigned char* ws, int xnrow0, const float* DECB, int lchunk0, int nchunks, int h, int e, const float* s0, float* sout) {
;     ...
;         for (int q = 0; q < 4; ++q) if (n0 + q < nchunks) {
;             *(u32x4*)up[q] = (u32x4){pk2(S[0], S[1]), pk2(S[2], S[3]), pk2(S[4], S[5]), pk2(S[6], S[7])};
;             S[0] = d0[q][0] * (S[0] + bflo(uw[q].x)); S[1] = d0[q][1] * (S[1] + bfhi(uw[q].x)); S[2] = d0[q][2] * (S[2] + bflo(uw[q].y)); S[3] = d0[q][3] * (S[3] + bfhi(uw[q].y));
;             S[4] = d1[q][0] * (S[4] + bflo(uw[q].z)); S[5] = d1[q][1] * (S[5] + bfhi(uw[q].z)); S[6] = d1[q][2] * (S[6] + bflo(uw[q].w)); S[7] = d1[q][3] * (S[7] + bfhi(uw[q].w)); }
.Lscan_w1:
	v_lshlrev_b32_e32 v82, 16, v78
	v_and_b32_e32 v83, 0xffff0000, v78
	v_lshlrev_b32_e32 v78, 16, v79
	v_and_b32_e32 v79, 0xffff0000, v79
	v_lshlrev_b32_e32 v84, 16, v80
	v_and_b32_e32 v85, 0xffff0000, v80
	v_lshlrev_b32_e32 v80, 16, v81
	v_and_b32_e32 v81, 0xffff0000, v81
	v_pk_add_f32 v[26:27], v[26:27], v[82:83]
	v_pk_add_f32 v[24:25], v[24:25], v[78:79]
	v_pk_add_f32 v[84:85], v[22:23], v[84:85]
	v_pk_add_f32 v[80:81], v[20:21], v[80:81]
	v_pk_mul_f32 v[82:83], v[74:75], v[26:27]
	v_pk_mul_f32 v[78:79], v[76:77], v[24:25]
	v_pk_mul_f32 v[22:23], v[70:71], v[84:85]
	v_pk_mul_f32 v[92:93], v[72:73], v[80:81]
	v_cvt_pk_bf16_f32 v20, v82, v83
	v_cvt_pk_bf16_f32 v21, v78, v79
	v_cvt_pk_bf16_f32 v22, v22, v23
	v_cvt_pk_bf16_f32 v23, v92, v93
	global_store_dwordx4 v[86:87], v[20:23], off
	s_nop 1
	v_lshlrev_b32_e32 v20, 16, v34
	v_and_b32_e32 v21, 0xffff0000, v34
	v_lshlrev_b32_e32 v22, 16, v35
	v_and_b32_e32 v23, 0xffff0000, v35
	v_lshlrev_b32_e32 v34, 16, v36
	v_and_b32_e32 v35, 0xffff0000, v36
	v_lshlrev_b32_e32 v36, 16, v37
	v_and_b32_e32 v37, 0xffff0000, v37
	v_pk_fma_f32 v[26:27], v[74:75], v[26:27], v[20:21]
	v_pk_fma_f32 v[24:25], v[76:77], v[24:25], v[22:23]
	v_pk_fma_f32 v[34:35], v[70:71], v[84:85], v[34:35]
	v_pk_fma_f32 v[36:37], v[72:73], v[80:81], v[36:37]
	v_pk_mul_f32 v[20:21], v[38:39], v[26:27]
	v_pk_mul_f32 v[22:23], v[40:41], v[24:25]
	v_pk_mul_f32 v[70:71], v[42:43], v[34:35]
	v_pk_mul_f32 v[72:73], v[44:45], v[36:37]
	v_cvt_pk_bf16_f32 v20, v20, v21
	v_cvt_pk_bf16_f32 v21, v22, v23
	v_cvt_pk_bf16_f32 v22, v70, v71
	v_cvt_pk_bf16_f32 v23, v72, v73
	global_store_dwordx4 v[88:89], v[20:23], off
	s_nop 1
	v_lshlrev_b32_e32 v20, 16, v46
	v_and_b32_e32 v21, 0xffff0000, v46
	v_lshlrev_b32_e32 v22, 16, v47
	v_and_b32_e32 v23, 0xffff0000, v47
	v_pk_fma_f32 v[26:27], v[38:39], v[26:27], v[20:21]
	v_pk_fma_f32 v[24:25], v[40:41], v[24:25], v[22:23]
	v_lshlrev_b32_e32 v38, 16, v48
	v_and_b32_e32 v39, 0xffff0000, v48
	v_lshlrev_b32_e32 v40, 16, v49
	v_and_b32_e32 v41, 0xffff0000, v49
	v_pk_fma_f32 v[34:35], v[42:43], v[34:35], v[38:39]
	v_pk_fma_f32 v[36:37], v[44:45], v[36:37], v[40:41]
	v_pk_mul_f32 v[20:21], v[50:51], v[26:27]
	v_pk_mul_f32 v[22:23], v[52:53], v[24:25]
	v_pk_mul_f32 v[38:39], v[54:55], v[34:35]
	v_pk_mul_f32 v[40:41], v[56:57], v[36:37]
	v_cvt_pk_bf16_f32 v20, v20, v21
	v_cvt_pk_bf16_f32 v21, v22, v23
	v_cvt_pk_bf16_f32 v22, v38, v39
	v_cvt_pk_bf16_f32 v23, v40, v41
	global_store_dwordx4 v[90:91], v[20:23], off
	s_nop 1
	v_lshlrev_b32_e32 v20, 16, v58
	v_and_b32_e32 v21, 0xffff0000, v58
	v_pk_fma_f32 v[20:21], v[50:51], v[26:27], v[20:21]
	s_nop 0
	v_pk_mul_f32 v[26:27], v[62:63], v[20:21]
	v_lshlrev_b32_e32 v20, 16, v59
	v_and_b32_e32 v21, 0xffff0000, v59
	v_pk_fma_f32 v[20:21], v[52:53], v[24:25], v[20:21]
	s_nop 0
	v_pk_mul_f32 v[24:25], v[64:65], v[20:21]
	v_lshlrev_b32_e32 v20, 16, v60
	v_and_b32_e32 v21, 0xffff0000, v60
	v_pk_fma_f32 v[20:21], v[54:55], v[34:35], v[20:21]
	s_nop 0
	v_pk_mul_f32 v[22:23], v[66:67], v[20:21]
	v_lshlrev_b32_e32 v20, 16, v61
	v_and_b32_e32 v21, 0xffff0000, v61
	v_pk_fma_f32 v[20:21], v[56:57], v[36:37], v[20:21]
	s_nop 0
	v_pk_mul_f32 v[20:21], v[68:69], v[20:21]
	s_cmp_eq_u32 s2, 3
	s_cbranch_scc1 .Lscan_last
	v_lshl_add_u64 v[38:39], v[12:13], 0, s[12:13]
	v_add_co_u32_e32 v42, vcc, s73, v38
	v_lshl_add_u64 v[50:51], v[8:9], 0, s[12:13]
	s_nop 0
	v_addc_co_u32_e32 v43, vcc, 0, v39, vcc
	v_add_co_u32_e32 v54, vcc, s73, v50
	v_lshl_add_u64 v[62:63], v[4:5], 0, s[12:13]
	s_nop 0
	v_addc_co_u32_e32 v55, vcc, 0, v51, vcc
	v_add_co_u32_e32 v66, vcc, s73, v62
	v_lshl_add_u64 v[70:71], v[18:19], 0, s[12:13]
	s_nop 0
	v_addc_co_u32_e32 v67, vcc, 0, v63, vcc
	v_add_co_u32_e32 v74, vcc, s73, v70
	v_lshl_add_u64 v[86:87], v[14:15], 0, s[12:13]
	v_lshl_add_u64 v[88:89], v[10:11], 0, s[12:13]
	v_lshl_add_u64 v[90:91], v[6:7], 0, s[12:13]
	v_addc_co_u32_e32 v75, vcc, 0, v71, vcc
	v_lshl_add_u64 v[92:93], v[16:17], 0, s[12:13]
	global_load_dwordx4 v[34:37], v[86:87], off
	global_load_dwordx4 v[38:41], v[42:43], off
	s_nop 0
	global_load_dwordx4 v[42:45], v[42:43], off offset:32
	global_load_dwordx4 v[46:49], v[88:89], off
	global_load_dwordx4 v[50:53], v[54:55], off
	s_nop 0
	global_load_dwordx4 v[54:57], v[54:55], off offset:32
	global_load_dwordx4 v[58:61], v[90:91], off
	global_load_dwordx4 v[62:65], v[66:67], off
	s_nop 0
	global_load_dwordx4 v[66:69], v[66:67], off offset:32
	s_nop 0
	global_load_dwordx4 v[70:73], v[74:75], off offset:32
	s_nop 0
	global_load_dwordx4 v[74:77], v[74:75], off
	global_load_dwordx4 v[78:81], v[92:93], off
	v_lshl_add_u64 v[4:5], v[4:5], 0, s[86:87]
	v_lshl_add_u64 v[6:7], v[6:7], 0, s[84:85]
	v_lshl_add_u64 v[8:9], v[8:9], 0, s[86:87]
	v_lshl_add_u64 v[10:11], v[10:11], 0, s[84:85]
	v_lshl_add_u64 v[12:13], v[12:13], 0, s[86:87]
	v_lshl_add_u64 v[14:15], v[14:15], 0, s[84:85]
	v_lshl_add_u64 v[16:17], v[16:17], 0, s[84:85]
	v_lshl_add_u64 v[18:19], v[18:19], 0, s[86:87]
	v_cvt_pk_bf16_f32 v82, v26, v27
	v_cvt_pk_bf16_f32 v83, v24, v25
	v_cvt_pk_bf16_f32 v84, v22, v23
	v_cvt_pk_bf16_f32 v85, v20, v21
	global_store_dwordx4 v[248:249], v[82:85], off
	s_nop 1
	s_waitcnt vmcnt(17)
	s_branch .Lscan_w2
; __device__ __forceinline__ unsigned pk2(float lo, float hi) { return pg8::cvt_pk_bf16(lo, hi); }
; __device__ __forceinline__ float bflo(unsigned w) { return __uint_as_float(w << 16); }
; __device__ __forceinline__ float bfhi(unsigned w) { return __uint_as_float(w & 0xffff0000u); }
; __device__ __forceinline__ void gla_scan_vec(unsigned char* ws, int xnrow0, const float* DECB, int lchunk0, int nchunks, int h, int e, const float* s0, float* sout) {
;     ...
;         for (int q = 0; q < 4; ++q) if (n0 + q < nchunks) {
;             *(u32x4*)up[q] = (u32x4){pk2(S[0], S[1]), pk2(S[2], S[3]), pk2(S[4], S[5]), pk2(S[6], S[7])};
;             S[0] = d0[q][0] * (S[0] + bflo(uw[q].x)); S[1] = d0[q][1] * (S[1] + bfhi(uw[q].x)); S[2] = d0[q][2] * (S[2] + bflo(uw[q].y)); S[3] = d0[q][3] * (S[3] + bfhi(uw[q].y));
;             S[4] = d1[q][0] * (S[4] + bflo(uw[q].z)); S[5] = d1[q][1] * (S[5] + bfhi(uw[q].z)); S[6] = d1[q][2] * (S[6] + bflo(uw[q].w)); S[7] = d1[q][3] * (S[7] + bfhi(uw[q].w)); }
;     }
; #pragma unroll
;     for (int jj = 0; jj < 8; ++jj) __builtin_nontemporal_store(S[jj], sout + (size_t)(dbase + 8 * (jj >> 2) + (jj & 3)) * 256 + v);
.Lscan_last:
	v_cvt_pk_bf16_f32 v82, v26, v27
	v_cvt_pk_bf16_f32 v83, v24, v25
	v_cvt_pk_bf16_f32 v84, v22, v23
	v_cvt_pk_bf16_f32 v85, v20, v21
	global_store_dwordx4 v[248:249], v[82:85], off
	s_nop 1
	s_waitcnt vmcnt(5)
.Lscan_w2:
	v_lshlrev_b32_e32 v82, 16, v242
	v_and_b32_e32 v83, 0xffff0000, v242
	v_lshlrev_b32_e32 v242, 16, v243
	v_and_b32_e32 v243, 0xffff0000, v243
	v_lshlrev_b32_e32 v84, 16, v244
	v_and_b32_e32 v85, 0xffff0000, v244
	v_lshlrev_b32_e32 v244, 16, v245
	v_and_b32_e32 v245, 0xffff0000, v245
	v_pk_add_f32 v[26:27], v[26:27], v[82:83]
	v_pk_add_f32 v[24:25], v[24:25], v[242:243]
	v_pk_add_f32 v[84:85], v[22:23], v[84:85]
	v_pk_add_f32 v[244:245], v[20:21], v[244:245]
	v_pk_mul_f32 v[82:83], v[238:239], v[26:27]
	v_pk_mul_f32 v[242:243], v[240:241], v[24:25]
	v_pk_mul_f32 v[22:23], v[234:235], v[84:85]
	v_pk_mul_f32 v[248:249], v[236:237], v[244:245]
	v_cvt_pk_bf16_f32 v20, v82, v83
	v_cvt_pk_bf16_f32 v21, v242, v243
	v_cvt_pk_bf16_f32 v22, v22, v23
	v_cvt_pk_bf16_f32 v23, v248, v249
	global_store_dwordx4 v[178:179], v[20:23], off
	s_nop 1
	v_lshlrev_b32_e32 v20, 16, v170
	v_and_b32_e32 v21, 0xffff0000, v170
	v_lshlrev_b32_e32 v22, 16, v171
	v_and_b32_e32 v23, 0xffff0000, v171
	v_lshlrev_b32_e32 v170, 16, v172
	v_and_b32_e32 v171, 0xffff0000, v172
	v_lshlrev_b32_e32 v172, 16, v173
	v_and_b32_e32 v173, 0xffff0000, v173
	v_pk_fma_f32 v[26:27], v[238:239], v[26:27], v[20:21]
	v_pk_fma_f32 v[24:25], v[240:241], v[24:25], v[22:23]
	v_pk_fma_f32 v[170:171], v[234:235], v[84:85], v[170:171]
	v_pk_fma_f32 v[172:173], v[236:237], v[244:245], v[172:173]
	v_pk_mul_f32 v[20:21], v[174:175], v[26:27]
	v_pk_mul_f32 v[22:23], v[176:177], v[24:25]
	v_pk_mul_f32 v[234:235], v[182:183], v[170:171]
	v_pk_mul_f32 v[236:237], v[184:185], v[172:173]
	v_cvt_pk_bf16_f32 v20, v20, v21
	v_cvt_pk_bf16_f32 v21, v22, v23
	v_cvt_pk_bf16_f32 v22, v234, v235
	v_cvt_pk_bf16_f32 v23, v236, v237
	global_store_dwordx4 v[194:195], v[20:23], off
	s_nop 1
	v_lshlrev_b32_e32 v20, 16, v186
	v_and_b32_e32 v21, 0xffff0000, v186
	v_lshlrev_b32_e32 v22, 16, v187
	v_and_b32_e32 v23, 0xffff0000, v187
	v_pk_fma_f32 v[26:27], v[174:175], v[26:27], v[20:21]
	v_pk_fma_f32 v[24:25], v[176:177], v[24:25], v[22:23]
	v_lshlrev_b32_e32 v174, 16, v188
	v_and_b32_e32 v175, 0xffff0000, v188
	v_lshlrev_b32_e32 v176, 16, v189
	v_and_b32_e32 v177, 0xffff0000, v189
	v_pk_fma_f32 v[170:171], v[182:183], v[170:171], v[174:175]
	v_pk_fma_f32 v[172:173], v[184:185], v[172:173], v[176:177]
	v_pk_mul_f32 v[20:21], v[190:191], v[26:27]
	v_pk_mul_f32 v[22:23], v[192:193], v[24:25]
	v_pk_mul_f32 v[174:175], v[218:219], v[170:171]
	v_pk_mul_f32 v[176:177], v[220:221], v[172:173]
	v_cvt_pk_bf16_f32 v20, v20, v21
	v_cvt_pk_bf16_f32 v21, v22, v23
	v_cvt_pk_bf16_f32 v22, v174, v175
	v_cvt_pk_bf16_f32 v23, v176, v177
	global_store_dwordx4 v[246:247], v[20:23], off
	s_nop 1
	v_lshlrev_b32_e32 v20, 16, v222
	v_and_b32_e32 v21, 0xffff0000, v222
	v_pk_fma_f32 v[20:21], v[190:191], v[26:27], v[20:21]
	s_nop 0
	v_pk_mul_f32 v[26:27], v[226:227], v[20:21]
	v_lshlrev_b32_e32 v20, 16, v223
	v_and_b32_e32 v21, 0xffff0000, v223
	v_pk_fma_f32 v[20:21], v[192:193], v[24:25], v[20:21]
	s_nop 0
	v_pk_mul_f32 v[24:25], v[228:229], v[20:21]
	v_lshlrev_b32_e32 v20, 16, v224
	v_and_b32_e32 v21, 0xffff0000, v224
	v_pk_fma_f32 v[20:21], v[218:219], v[170:171], v[20:21]
	s_nop 0
	v_pk_mul_f32 v[22:23], v[230:231], v[20:21]
	v_lshlrev_b32_e32 v20, 16, v225
	v_and_b32_e32 v21, 0xffff0000, v225
	v_pk_fma_f32 v[20:21], v[220:221], v[172:173], v[20:21]
	s_nop 0
	v_pk_mul_f32 v[20:21], v[232:233], v[20:21]
	s_add_i32 s2, s2, 1
	s_cmp_lt_u32 s2, 4
	s_cbranch_scc1 .Lscan_pipe
	v_readlane_b32 s0, v251, 58
	v_lshrrev_b32_e32 v6, 3, v32
	v_and_b32_e32 v6, 4, v6
	v_lshl_add_u32 v4, v33, 2, s0
	v_and_or_b32 v4, v2, 3, v4
	v_lshrrev_b32_e32 v2, 2, v32
	s_movk_i32 s0, 0x70
	v_ashrrev_i32_e32 v5, 31, v4
	v_and_or_b32 v6, v2, s0, v6
	v_lshrrev_b32_e32 v2, 4, v32
	s_movk_i32 s0, 0xe0
	v_lshlrev_b64 v[4:5], 17, v[4:5]
	v_and_or_b32 v2, v2, s0, v29
	v_lshl_add_u64 v[4:5], s[16:17], 0, v[4:5]
	v_lshlrev_b32_e32 v2, 2, v2
	v_lshl_add_u64 v[4:5], v[4:5], 0, v[2:3]
	v_lshlrev_b32_e32 v2, 10, v6
	v_lshl_add_u64 v[4:5], v[4:5], 0, v[2:3]
	global_store_dword v[4:5], v26, off nt
	global_store_dword v[4:5], v27, off offset:1024 nt
	global_store_dword v[4:5], v24, off offset:2048 nt
	global_store_dword v[4:5], v25, off offset:3072 nt
	v_add_co_u32_e32 v4, vcc, 0x2000, v4
	v_readlane_b32 s0, v251, 11
	s_nop 0
	v_addc_co_u32_e32 v5, vcc, 0, v5, vcc
	v_add_u32_e32 v32, s0, v32
	s_mov_b32 s0, 0x1ffff
	v_cmp_lt_i32_e32 vcc, s0, v32
	v_readlane_b32 s0, v251, 40
	s_or_b64 s[18:19], vcc, s[18:19]
	global_store_dword v[4:5], v22, off nt
	global_store_dword v[4:5], v23, off offset:1024 nt
	global_store_dword v[4:5], v20, off offset:2048 nt
	global_store_dword v[4:5], v21, off offset:3072 nt
	v_add_u32_e32 v31, s0, v31
	s_andn2_b64 exec, exec, s[18:19]
	s_cbranch_execnz .LBB0_618

; template <class Epi, class Sched, bool ALIGN_EPI = false, bool SP2 = false>
; __device__ __forceinline__ void gemm_phase(PG8_LAS unsigned char* lds, const Gemm g, const Sched& S, const Epi& E, const int tid_arg) {
;     ...
;         const bool has_next = S.next(ui + 1, nxt);
;         const char* nA = has_next ? (const char*)g.A + (size_t)nxt.pm * tstep : cA; const char* nB = has_next ? (const char*)g.Bt + (size_t)nxt.pn * tstep : cB;
;         for (int t = 0; t < nt; t += 2) {
;             const bool last = (t == nt - 2);
;             const char* a1 = cA + (size_t)(t + 1) * kstep;
;             const char* a2 = last ? nA : cA + (size_t)(t + 2) * kstep; const char* b2 = last ? nB : cB + (size_t)(t + 2) * kstep;
;             const char* a3 = a2 + kstep; const char* b3 = b2 + kstep;
;     ...
; #pragma unroll
;         for (int a = 0; a < 2; ++a)
; #pragma unroll
;             for (int b = 0; b < 2; ++b)
; #pragma unroll
;                 for (int m = 0; m < 4; ++m)
; #pragma unroll
;                     for (int n = 0; n < 2; ++n) acc[a][b][m][n] = (f32x4){0.f, 0.f, 0.f, 0.f};
;         cur = nxt; cA = nA; cB = nB; ++ui;
.LBB0_763:
	s_ashr_i32 s27, s26, 31
	s_lshl_b64 s[28:29], s[26:27], 19
	s_add_u32 s28, s3, s28
	s_addc_u32 s29, s6, s29
	s_and_b64 s[30:31], s[10:11], exec
	s_cselect_b32 s27, s29, s5
	s_cselect_b32 s48, s28, s4
	s_ashr_i32 s25, s24, 31
	s_lshl_b64 s[30:31], s[24:25], 19
	s_add_u32 s30, s7, s30
	s_addc_u32 s31, s38, s31
	s_and_b64 s[36:37], s[10:11], exec
	s_cselect_b32 s25, s31, s35
	s_cselect_b32 s49, s30, s34
	s_add_u32 s4, s4, 0x40080
	s_addc_u32 s5, s5, 0
	s_add_u32 s50, s34, 0x100
	v_mov_b32_e32 v4, 0
	s_addc_u32 s51, s35, 0
	s_mov_b32 s52, -2
	v_mov_b32_e32 v5, v4
	v_mov_b32_e32 v6, v4
	v_mov_b32_e32 v7, v4
	v_mov_b32_e32 v8, v4
	v_mov_b32_e32 v9, v4
	v_mov_b32_e32 v10, v4
	v_mov_b32_e32 v11, v4
	v_mov_b32_e32 v20, v4
	v_mov_b32_e32 v21, v4
	v_mov_b32_e32 v22, v4
	v_mov_b32_e32 v23, v4
	v_mov_b32_e32 v24, v4
	v_mov_b32_e32 v25, v4
	v_mov_b32_e32 v26, v4
	v_mov_b32_e32 v27, v4
	v_mov_b32_e32 v36, v4
	v_mov_b32_e32 v37, v4
	v_mov_b32_e32 v38, v4
	v_mov_b32_e32 v39, v4
	v_mov_b32_e32 v40, v4
	v_mov_b32_e32 v41, v4
	v_mov_b32_e32 v42, v4
	v_mov_b32_e32 v43, v4
	v_mov_b32_e32 v52, v4
	v_mov_b32_e32 v53, v4
	v_mov_b32_e32 v54, v4
	v_mov_b32_e32 v55, v4
	v_mov_b32_e32 v56, v4
	v_mov_b32_e32 v57, v4
	v_mov_b32_e32 v58, v4
	v_mov_b32_e32 v59, v4
	v_mov_b32_e32 v12, v4
	v_mov_b32_e32 v13, v4
	v_mov_b32_e32 v14, v4
	v_mov_b32_e32 v15, v4
	v_mov_b32_e32 v16, v4
	v_mov_b32_e32 v17, v4
	v_mov_b32_e32 v18, v4
	v_mov_b32_e32 v19, v4
	v_mov_b32_e32 v28, v4
	v_mov_b32_e32 v29, v4
	v_mov_b32_e32 v30, v4
	v_mov_b32_e32 v31, v4
	v_mov_b32_e32 v32, v4
	v_mov_b32_e32 v33, v4
	v_mov_b32_e32 v34, v4
	v_mov_b32_e32 v35, v4
	v_mov_b32_e32 v44, v4
	v_mov_b32_e32 v45, v4
	v_mov_b32_e32 v46, v4
	v_mov_b32_e32 v47, v4
	v_mov_b32_e32 v48, v4
	v_mov_b32_e32 v49, v4
	v_mov_b32_e32 v50, v4
	v_mov_b32_e32 v51, v4
	v_mov_b32_e32 v60, v4
	v_mov_b32_e32 v61, v4
	v_mov_b32_e32 v62, v4
	v_mov_b32_e32 v63, v4
	v_mov_b32_e32 v64, v4
	v_mov_b32_e32 v65, v4
	v_mov_b32_e32 v66, v4
	v_mov_b32_e32 v67, v4
	v_mov_b32_e32 v68, v4
	v_mov_b32_e32 v69, v4
	v_mov_b32_e32 v70, v4
	v_mov_b32_e32 v71, v4
	v_mov_b32_e32 v72, v4
	v_mov_b32_e32 v73, v4
	v_mov_b32_e32 v74, v4
	v_mov_b32_e32 v75, v4
	v_mov_b32_e32 v84, v4
	v_mov_b32_e32 v85, v4
	v_mov_b32_e32 v86, v4
	v_mov_b32_e32 v87, v4
	v_mov_b32_e32 v88, v4
	v_mov_b32_e32 v89, v4
	v_mov_b32_e32 v90, v4
	v_mov_b32_e32 v91, v4
	v_mov_b32_e32 v100, v4
	v_mov_b32_e32 v101, v4
	v_mov_b32_e32 v102, v4
	v_mov_b32_e32 v103, v4
	v_mov_b32_e32 v104, v4
	v_mov_b32_e32 v105, v4
	v_mov_b32_e32 v106, v4
	v_mov_b32_e32 v107, v4
	v_mov_b32_e32 v116, v4
	v_mov_b32_e32 v117, v4
	v_mov_b32_e32 v118, v4
	v_mov_b32_e32 v119, v4
	s_waitcnt vmcnt(0)
	v_mov_b32_e32 v120, v4
	v_mov_b32_e32 v121, v4
	v_mov_b32_e32 v122, v4
	v_mov_b32_e32 v123, v4
	v_mov_b32_e32 v76, v4
	v_mov_b32_e32 v77, v4
	v_mov_b32_e32 v78, v4
	v_mov_b32_e32 v79, v4
	v_mov_b32_e32 v80, v4
	v_mov_b32_e32 v81, v4
	v_mov_b32_e32 v82, v4
	v_mov_b32_e32 v83, v4
	v_mov_b32_e32 v92, v4
	v_mov_b32_e32 v93, v4
	v_mov_b32_e32 v94, v4
	v_mov_b32_e32 v95, v4
	v_mov_b32_e32 v96, v4
	v_mov_b32_e32 v97, v4
	v_mov_b32_e32 v98, v4
	v_mov_b32_e32 v99, v4
	v_mov_b32_e32 v108, v4
	v_mov_b32_e32 v109, v4
	v_mov_b32_e32 v110, v4
	v_mov_b32_e32 v111, v4
	v_mov_b32_e32 v112, v4
	v_mov_b32_e32 v113, v4
	v_mov_b32_e32 v114, v4
	v_mov_b32_e32 v115, v4
	v_mov_b32_e32 v124, v4
	v_mov_b32_e32 v125, v4
	v_mov_b32_e32 v126, v4
	v_mov_b32_e32 v127, v4
	v_mov_b32_e32 v128, v4
	v_mov_b32_e32 v129, v4
	v_mov_b32_e32 v130, v4
	v_mov_b32_e32 v131, v4
	s_nop 0
	s_nop 0
	s_nop 0
	s_nop 0
	s_nop 0
	s_nop 0
	s_nop 0
	s_nop 0
	s_nop 0
	s_nop 0
	s_nop 0
